# proj GEMM loops: per-K-step s_setprio toggles replaced by one static priority raise for the half of the blocks with li bit5 (co-resident partner stays at 0)
# speedup vs baseline: 1.0071x; 1.0054x over previous
; DEVI void phase_gemm_big(const Params& p, int mode, bf16_t* smem) {
;     ...
;   for (int L = li; L < per_xcd; L += nli) {
;     const int mg = L / (8 * NT), rem = L % (8 * NT), nt = rem >> 3, mt = xcd * 40 + mg * 8 + (rem & 7), m0 = mt * 256, n0 = nt * 128;
;     const int Ln = L + nli < per_xcd ? L + nli : L;
;     const int mgn = Ln / (8 * NT), remn = Ln % (8 * NT), m0n = (xcd * 40 + mgn * 8 + (remn & 7)) * 256, n0n = (remn >> 3) * 128;
;     f32x4 acc[8][4];
; #pragma unroll
;     for (int i = 0; i < 8; ++i)
; #pragma unroll
;       for (int j = 0; j < 4; ++j) acc[i][j] = (f32x4){0.f, 0.f, 0.f, 0.f};
;     gemm_kloop2(Abase + (size_t)m0 * 1024, 1024, Bbase + (size_t)n0 * 1024, 1024,
;                 Abase + (size_t)m0n * 1024, 1024, Bbase + (size_t)n0n * 1024, 1024, first, smem, acc);
.Lg1_go:
	s_add_u32 s86, s42, 0x80
	s_addc_u32 s87, s43, 0
	s_add_u32 s56, s44, 0x80
	s_addc_u32 s57, s45, 0
	s_add_i32 s35, s41, s83
	s_cmpk_gt_i32 s35, 0x54f
	s_cselect_b64 s[38:39], -1, 0
	s_cmpk_lt_i32 s35, 0x550
	s_cselect_b32 s2, s35, s41
	s_mul_hi_i32 s3, s2, 0x78787879
	s_lshr_b32 s37, s3, 31
	s_ashr_i32 s3, s3, 7
	s_add_i32 s3, s3, s37
	s_mul_i32 s37, s3, 0x110
	s_sub_i32 s2, s2, s37
	s_lshl_b32 s3, s3, 3
	s_add_i32 s3, s3, s40
	s_and_b32 s37, s2, 7
	s_or_b32 s3, s3, s37
	s_lshl_b32 s37, s2, 4
	s_lshl_b32 s2, s3, 8
	s_ashr_i32 s3, s2, 31
	s_and_b32 s42, s37, 0xffffff80
	s_lshl_b64 s[2:3], s[2:3], 11
	s_add_u32 s2, s20, s2
	s_addc_u32 s3, s21, s3
	s_ashr_i32 s43, s42, 31
	s_lshl_b64 s[42:43], s[42:43], 11
	s_add_u32 s42, s0, s42
	s_addc_u32 s43, s1, s43
	s_mov_b64 s[58:59], s[2:3]
	s_mov_b64 s[60:61], s[42:43]
	s_mov_b32 s65, 0
	s_bitcmp1_b32 s41, 5
	s_cbranch_scc0 .Lg1_np
	s_setprio 1
.Lg1_np:
	v_mov_b32_e32 v2, 0
	v_mov_b32_e32 v3, v2
	v_mov_b32_e32 v4, v2
	v_mov_b32_e32 v5, v2
	v_mov_b32_e32 v6, v2
	v_mov_b32_e32 v7, v2
	v_mov_b32_e32 v8, v2
	v_mov_b32_e32 v9, v2
	v_mov_b32_e32 v10, v2
	v_mov_b32_e32 v11, v2
	v_mov_b32_e32 v12, v2
	v_mov_b32_e32 v13, v2
	v_mov_b32_e32 v14, v2
	v_mov_b32_e32 v15, v2
	v_mov_b32_e32 v16, v2
	v_mov_b32_e32 v17, v2
	v_mov_b32_e32 v18, v2
	v_mov_b32_e32 v19, v2
	v_mov_b32_e32 v20, v2
	v_mov_b32_e32 v21, v2
	v_mov_b32_e32 v22, v2
	v_mov_b32_e32 v23, v2
	v_mov_b32_e32 v24, v2
	v_mov_b32_e32 v25, v2
	v_mov_b32_e32 v26, v2
	v_mov_b32_e32 v27, v2
	v_mov_b32_e32 v28, v2
	v_mov_b32_e32 v29, v2
	v_mov_b32_e32 v30, v2
	v_mov_b32_e32 v31, v2
	v_mov_b32_e32 v32, v2
	v_mov_b32_e32 v33, v2
	v_mov_b32_e32 v34, v2
	v_mov_b32_e32 v35, v2
	v_mov_b32_e32 v36, v2
	v_mov_b32_e32 v37, v2
	v_mov_b32_e32 v38, v2
	v_mov_b32_e32 v39, v2
	v_mov_b32_e32 v40, v2
	v_mov_b32_e32 v41, v2
	v_mov_b32_e32 v42, v2
	v_mov_b32_e32 v43, v2
	v_mov_b32_e32 v44, v2
	v_mov_b32_e32 v45, v2
	v_mov_b32_e32 v46, v2
	v_mov_b32_e32 v47, v2
	v_mov_b32_e32 v48, v2
	v_mov_b32_e32 v49, v2
	v_mov_b32_e32 v50, v2
	v_mov_b32_e32 v51, v2
	v_mov_b32_e32 v52, v2
	v_mov_b32_e32 v53, v2
	v_mov_b32_e32 v54, v2
	v_mov_b32_e32 v55, v2
	v_mov_b32_e32 v56, v2
	v_mov_b32_e32 v57, v2
	v_mov_b32_e32 v58, v2
	v_mov_b32_e32 v59, v2
	v_mov_b32_e32 v60, v2
	v_mov_b32_e32 v61, v2
	v_mov_b32_e32 v62, v2
	v_mov_b32_e32 v63, v2
	v_mov_b32_e32 v64, v2
	v_mov_b32_e32 v65, v2
	v_mov_b32_e32 v66, v2
	v_mov_b32_e32 v67, v2
	v_mov_b32_e32 v68, v2
	v_mov_b32_e32 v69, v2
	v_mov_b32_e32 v70, v2
	v_mov_b32_e32 v71, v2
	v_mov_b32_e32 v72, v2
	v_mov_b32_e32 v73, v2
	v_mov_b32_e32 v74, v2
	v_mov_b32_e32 v75, v2
	v_mov_b32_e32 v76, v2
	v_mov_b32_e32 v77, v2
	v_mov_b32_e32 v78, v2
	v_mov_b32_e32 v79, v2
	v_mov_b32_e32 v80, v2
	v_mov_b32_e32 v81, v2
	v_mov_b32_e32 v82, v2
	v_mov_b32_e32 v83, v2
	v_mov_b32_e32 v84, v2
	v_mov_b32_e32 v85, v2
	v_mov_b32_e32 v86, v2
	v_mov_b32_e32 v87, v2
	v_mov_b32_e32 v88, v2
	v_mov_b32_e32 v89, v2
	v_mov_b32_e32 v90, v2
	v_mov_b32_e32 v91, v2
	v_mov_b32_e32 v92, v2
	v_mov_b32_e32 v93, v2
	v_mov_b32_e32 v94, v2
	v_mov_b32_e32 v95, v2
	v_mov_b32_e32 v96, v2
	v_mov_b32_e32 v97, v2
	v_mov_b32_e32 v98, v2
	v_mov_b32_e32 v99, v2
	v_mov_b32_e32 v100, v2
	v_mov_b32_e32 v101, v2
	v_mov_b32_e32 v102, v2
	v_mov_b32_e32 v103, v2
	v_mov_b32_e32 v104, v2
	v_mov_b32_e32 v105, v2
	v_mov_b32_e32 v106, v2
	v_mov_b32_e32 v107, v2
	v_mov_b32_e32 v108, v2
	v_mov_b32_e32 v109, v2
	v_mov_b32_e32 v110, v2
	v_mov_b32_e32 v111, v2
	v_mov_b32_e32 v112, v2
	v_mov_b32_e32 v113, v2
	v_mov_b32_e32 v114, v2
	v_mov_b32_e32 v115, v2
	v_mov_b32_e32 v116, v2
	v_mov_b32_e32 v117, v2
	v_mov_b32_e32 v118, v2
	v_mov_b32_e32 v119, v2
	v_mov_b32_e32 v120, v2
	v_mov_b32_e32 v121, v2
	v_mov_b32_e32 v122, v2
	v_mov_b32_e32 v123, v2
	v_mov_b32_e32 v124, v2
	v_mov_b32_e32 v125, v2
	v_mov_b32_e32 v126, v2
	v_mov_b32_e32 v127, v2
	v_mov_b32_e32 v128, v2
	v_mov_b32_e32 v129, v2

.Lg1_wd:
	s_barrier
	v_add_u32_e32 v130, s50, v212
	v_add_u32_e32 v131, s50, v213
	s_xor_b32 s16, s50, 0x8000
	s_add_u32 m0, s16, s52
	ds_read_b128 v[236:239], v192
	ds_read_b128 v[240:243], v192 offset:2048
	ds_read_b128 v[244:247], v192 offset:4096
	ds_read_b128 v[146:149], v192 offset:6144
	ds_read_b128 v[150:153], v193
	ds_read_b128 v[154:157], v193 offset:2048
	ds_read_b128 v[158:161], v193 offset:4096
	ds_read_b128 v[162:165], v193 offset:6144
	ds_read_b128 v[168:171], v130
	ds_read_b128 v[172:175], v130 offset:2048
	ds_read_b128 v[176:179], v130 offset:4096
	ds_read_b128 v[180:183], v130 offset:6144
	ds_read_b128 v[184:187], v130 offset:8192
	ds_read_b128 v[188:191], v130 offset:10240
	ds_read_b128 v[228:231], v130 offset:12288
	global_load_lds_dwordx4 v200, s[86:87]
	global_load_lds_dwordx4 v201, s[86:87] offset:1024
	global_load_lds_dwordx4 v202, s[86:87] offset:2048
	global_load_lds_dwordx4 v203, s[86:87] offset:3072
	s_add_u32 m0, m0, 0x1000
	s_nop 0
	global_load_lds_dwordx4 v204, s[86:87]
	global_load_lds_dwordx4 v205, s[86:87] offset:1024
	global_load_lds_dwordx4 v206, s[86:87] offset:2048
	global_load_lds_dwordx4 v207, s[86:87] offset:3072
	s_waitcnt lgkmcnt(7)
	s_barrier
; DEVI void lds_barrier() { asm volatile("s_waitcnt lgkmcnt(0)\n\ts_barrier" ::: "memory"); }
; #define SSTORE2(P, buf_) do { \
;     *(uint4*)(wA + (buf_) * 256 * GS2) = P##a0; *(uint4*)(wA + (buf_) * 256 * GS2 + 64 * GS2) = P##a1; \
;     *(uint4*)(wA + (buf_) * 256 * GS2 + 128 * GS2) = P##a2; *(uint4*)(wA + (buf_) * 256 * GS2 + 192 * GS2) = P##a3; \
;     *(uint4*)(wB + (buf_) * 128 * GS2) = P##b0; *(uint4*)(wB + (buf_) * 128 * GS2 + 64 * GS2) = P##b1; } while (0)
; DEVI void gemm_kloop2(const bf16_t* __restrict__ A, size_t lda, const bf16_t* __restrict__ Bt, size_t ldb,
;                       const bf16_t* __restrict__ nA, size_t nlda, const bf16_t* __restrict__ nBt, size_t nldb,
;                       bool first, bf16_t* smem, f32x4 (&acc)[8][4]) {
;     ...
; #pragma unroll 1
;   for (int kt = 0; kt < nk - 2; kt += 2) {
;     COMPUTE2(0, GLOAD2(x, gA, gB, lda, ldb, kt + 1));
;     SSTORE2(x, 1);
;     lds_barrier();
;     COMPUTE2(1, GLOAD2(x, gA, gB, lda, ldb, kt + 2));
;     SSTORE2(x, 0);
;     lds_barrier();
;   }
	s_mov_b32 m0, s53
	s_nop 0
	global_load_lds_dwordx4 v208, s[56:57]
	global_load_lds_dwordx4 v209, s[56:57] offset:1024
	global_load_lds_dwordx4 v210, s[56:57] offset:2048
	global_load_lds_dwordx4 v211, s[56:57] offset:3072
	ds_read_b128 v[232:235], v130 offset:14336
	s_waitcnt lgkmcnt(7)
	v_mfma_f32_16x16x32_bf16 v[114:117], v[236:239], v[168:171], v[114:117]
	v_mfma_f32_16x16x32_bf16 v[102:105], v[240:243], v[168:171], v[102:105]
	v_mfma_f32_16x16x32_bf16 v[94:97], v[244:247], v[168:171], v[94:97]
	v_mfma_f32_16x16x32_bf16 v[86:89], v[146:149], v[168:171], v[86:89]
	s_waitcnt lgkmcnt(6)
	v_mfma_f32_16x16x32_bf16 v[126:129], v[236:239], v[172:175], v[126:129]
	v_mfma_f32_16x16x32_bf16 v[122:125], v[240:243], v[172:175], v[122:125]
	ds_read_b128 v[168:171], v131
	v_mfma_f32_16x16x32_bf16 v[118:121], v[244:247], v[172:175], v[118:121]
	v_mfma_f32_16x16x32_bf16 v[110:113], v[146:149], v[172:175], v[110:113]
	s_waitcnt lgkmcnt(6)
	v_mfma_f32_16x16x32_bf16 v[106:109], v[236:239], v[176:179], v[106:109]
	v_mfma_f32_16x16x32_bf16 v[98:101], v[240:243], v[176:179], v[98:101]
	ds_read_b128 v[172:175], v131 offset:2048
	v_mfma_f32_16x16x32_bf16 v[90:93], v[244:247], v[176:179], v[90:93]
	v_mfma_f32_16x16x32_bf16 v[82:85], v[146:149], v[176:179], v[82:85]
	s_waitcnt lgkmcnt(6)
	v_mfma_f32_16x16x32_bf16 v[78:81], v[236:239], v[180:183], v[78:81]
	v_mfma_f32_16x16x32_bf16 v[74:77], v[240:243], v[180:183], v[74:77]
	ds_read_b128 v[176:179], v131 offset:4096
	v_mfma_f32_16x16x32_bf16 v[70:73], v[244:247], v[180:183], v[70:73]
	v_mfma_f32_16x16x32_bf16 v[66:69], v[146:149], v[180:183], v[66:69]
	s_waitcnt lgkmcnt(6)
	v_mfma_f32_16x16x32_bf16 v[62:65], v[236:239], v[184:187], v[62:65]
	v_mfma_f32_16x16x32_bf16 v[58:61], v[240:243], v[184:187], v[58:61]
	ds_read_b128 v[180:183], v131 offset:6144
	v_mfma_f32_16x16x32_bf16 v[54:57], v[244:247], v[184:187], v[54:57]
	v_mfma_f32_16x16x32_bf16 v[50:53], v[146:149], v[184:187], v[50:53]
	s_waitcnt lgkmcnt(6)
	v_mfma_f32_16x16x32_bf16 v[46:49], v[236:239], v[188:191], v[46:49]
	v_mfma_f32_16x16x32_bf16 v[42:45], v[240:243], v[188:191], v[42:45]
	ds_read_b128 v[184:187], v131 offset:8192
	v_mfma_f32_16x16x32_bf16 v[38:41], v[244:247], v[188:191], v[38:41]
	v_mfma_f32_16x16x32_bf16 v[34:37], v[146:149], v[188:191], v[34:37]
	s_waitcnt lgkmcnt(6)
	v_mfma_f32_16x16x32_bf16 v[30:33], v[236:239], v[228:231], v[30:33]
	v_mfma_f32_16x16x32_bf16 v[26:29], v[240:243], v[228:231], v[26:29]
	ds_read_b128 v[188:191], v131 offset:10240
	v_mfma_f32_16x16x32_bf16 v[22:25], v[244:247], v[228:231], v[22:25]
	v_mfma_f32_16x16x32_bf16 v[18:21], v[146:149], v[228:231], v[18:21]
	s_waitcnt lgkmcnt(6)
	v_mfma_f32_16x16x32_bf16 v[14:17], v[236:239], v[232:235], v[14:17]
	v_mfma_f32_16x16x32_bf16 v[10:13], v[240:243], v[232:235], v[10:13]
	ds_read_b128 v[228:231], v131 offset:12288
	v_mfma_f32_16x16x32_bf16 v[6:9], v[244:247], v[232:235], v[6:9]
	v_mfma_f32_16x16x32_bf16 v[2:5], v[146:149], v[232:235], v[2:5]
	s_waitcnt lgkmcnt(6)
	v_mfma_f32_16x16x32_bf16 v[114:117], v[150:153], v[168:171], v[114:117]
	v_mfma_f32_16x16x32_bf16 v[102:105], v[154:157], v[168:171], v[102:105]
	ds_read_b128 v[232:235], v131 offset:14336
	v_mfma_f32_16x16x32_bf16 v[94:97], v[158:161], v[168:171], v[94:97]
	v_mfma_f32_16x16x32_bf16 v[86:89], v[162:165], v[168:171], v[86:89]
	s_add_u32 s86, s86, 0x80
	s_waitcnt lgkmcnt(6)
	v_mfma_f32_16x16x32_bf16 v[126:129], v[150:153], v[172:175], v[126:129]
	v_mfma_f32_16x16x32_bf16 v[122:125], v[154:157], v[172:175], v[122:125]
	v_mfma_f32_16x16x32_bf16 v[118:121], v[158:161], v[172:175], v[118:121]
	v_mfma_f32_16x16x32_bf16 v[110:113], v[162:165], v[172:175], v[110:113]
	s_addc_u32 s87, s87, 0
	s_waitcnt lgkmcnt(5)
	v_mfma_f32_16x16x32_bf16 v[106:109], v[150:153], v[176:179], v[106:109]
	v_mfma_f32_16x16x32_bf16 v[98:101], v[154:157], v[176:179], v[98:101]
	v_mfma_f32_16x16x32_bf16 v[90:93], v[158:161], v[176:179], v[90:93]
	v_mfma_f32_16x16x32_bf16 v[82:85], v[162:165], v[176:179], v[82:85]
	s_add_u32 s56, s56, 0x80
	s_waitcnt lgkmcnt(4)
	v_mfma_f32_16x16x32_bf16 v[78:81], v[150:153], v[180:183], v[78:81]
	v_mfma_f32_16x16x32_bf16 v[74:77], v[154:157], v[180:183], v[74:77]
	v_mfma_f32_16x16x32_bf16 v[70:73], v[158:161], v[180:183], v[70:73]
	v_mfma_f32_16x16x32_bf16 v[66:69], v[162:165], v[180:183], v[66:69]
	s_addc_u32 s57, s57, 0
	s_waitcnt lgkmcnt(3)
	v_mfma_f32_16x16x32_bf16 v[62:65], v[150:153], v[184:187], v[62:65]
	v_mfma_f32_16x16x32_bf16 v[58:61], v[154:157], v[184:187], v[58:61]
	v_mfma_f32_16x16x32_bf16 v[54:57], v[158:161], v[184:187], v[54:57]
	v_mfma_f32_16x16x32_bf16 v[50:53], v[162:165], v[184:187], v[50:53]
	s_xor_b32 s50, s50, 0x8000
	s_waitcnt lgkmcnt(2)
	v_mfma_f32_16x16x32_bf16 v[46:49], v[150:153], v[188:191], v[46:49]
	v_mfma_f32_16x16x32_bf16 v[42:45], v[154:157], v[188:191], v[42:45]
	v_mfma_f32_16x16x32_bf16 v[38:41], v[158:161], v[188:191], v[38:41]
	v_mfma_f32_16x16x32_bf16 v[34:37], v[162:165], v[188:191], v[34:37]
	s_add_u32 s65, s65, 1
	s_waitcnt lgkmcnt(1)
	v_mfma_f32_16x16x32_bf16 v[30:33], v[150:153], v[228:231], v[30:33]
	v_mfma_f32_16x16x32_bf16 v[26:29], v[154:157], v[228:231], v[26:29]
	v_mfma_f32_16x16x32_bf16 v[22:25], v[158:161], v[228:231], v[22:25]
	v_mfma_f32_16x16x32_bf16 v[18:21], v[162:165], v[228:231], v[18:21]
	s_cmp_eq_u32 s65, 15
	s_waitcnt lgkmcnt(0)
	v_mfma_f32_16x16x32_bf16 v[14:17], v[150:153], v[232:235], v[14:17]
	v_mfma_f32_16x16x32_bf16 v[10:13], v[154:157], v[232:235], v[10:13]
	v_mfma_f32_16x16x32_bf16 v[6:9], v[158:161], v[232:235], v[6:9]
	v_mfma_f32_16x16x32_bf16 v[2:5], v[162:165], v[232:235], v[2:5]
	s_cselect_b64 s[86:87], s[58:59], s[86:87]
	s_cselect_b64 s[56:57], s[60:61], s[56:57]
	s_cmp_lt_u32 s65, 16
	s_cbranch_scc1 .Lg1_loop
	s_setprio 0
	s_nop 7
	s_nop 3
	v_add_u32_e32 v130, s36, v142
	s_cmpk_gt_i32 s34, 0x10ff
	v_ashrrev_i32_e32 v131, 31, v130
	s_mov_b64 s[2:3], -1
	s_cbranch_scc1 .LBB0_207
	s_andn2_b64 vcc, exec, s[2:3]
	s_cbranch_vccnz .LBB0_200
	s_branch .LBB0_208

; DEVI void phase_gemm_big(const Params& p, int mode, bf16_t* smem) {
;     ...
;   for (int L = li; L < per_xcd; L += nli) {
;     const int mg = L / (8 * NT), rem = L % (8 * NT), nt = rem >> 3, mt = xcd * 40 + mg * 8 + (rem & 7), m0 = mt * 256, n0 = nt * 128;
;     const int Ln = L + nli < per_xcd ? L + nli : L;
;     const int mgn = Ln / (8 * NT), remn = Ln % (8 * NT), m0n = (xcd * 40 + mgn * 8 + (remn & 7)) * 256, n0n = (remn >> 3) * 128;
.Lg2_go:
	s_add_u32 s86, s42, 0x80
	s_addc_u32 s87, s43, 0
	s_add_u32 s56, s44, 0x80
	s_addc_u32 s57, s45, 0
	s_add_i32 s35, s41, s83
	s_cmpk_gt_i32 s35, 0x3e7
	s_cselect_b64 s[38:39], -1, 0
	s_cmpk_lt_i32 s35, 0x3e8
	s_cselect_b32 s2, s35, s41
	s_mul_hi_i32 s3, s2, 0x51eb851f
	s_lshr_b32 s37, s3, 31
	s_ashr_i32 s3, s3, 6
	s_add_i32 s3, s3, s37
	s_mul_i32 s37, s3, 0xc8
	s_sub_i32 s2, s2, s37
	s_lshl_b32 s3, s3, 3
	s_add_i32 s3, s3, s40
	s_and_b32 s37, s2, 7
	s_or_b32 s3, s3, s37
	s_lshl_b32 s37, s2, 4
	s_lshl_b32 s2, s3, 8
	s_ashr_i32 s3, s2, 31
	s_and_b32 s42, s37, 0xffffff80
	s_lshl_b64 s[2:3], s[2:3], 11
	s_add_u32 s2, s20, s2
	s_addc_u32 s3, s21, s3
	s_ashr_i32 s43, s42, 31
	s_lshl_b64 s[42:43], s[42:43], 11
	s_add_u32 s42, s0, s42
	s_addc_u32 s43, s1, s43
	s_mov_b64 s[58:59], s[2:3]
	s_mov_b64 s[60:61], s[42:43]
	s_mov_b32 s65, 0
	s_bitcmp1_b32 s41, 5
	s_cbranch_scc0 .Lg2_np
	s_setprio 1

.Lg2_wd:
	s_barrier
	v_add_u32_e32 v130, s50, v212
	v_add_u32_e32 v131, s50, v213
	s_xor_b32 s16, s50, 0x8000
	s_add_u32 m0, s16, s52
	ds_read_b128 v[236:239], v192
	ds_read_b128 v[240:243], v192 offset:2048
	ds_read_b128 v[244:247], v192 offset:4096
	ds_read_b128 v[146:149], v192 offset:6144
	ds_read_b128 v[150:153], v193
	ds_read_b128 v[154:157], v193 offset:2048
	ds_read_b128 v[158:161], v193 offset:4096
	ds_read_b128 v[162:165], v193 offset:6144
	ds_read_b128 v[168:171], v130
	ds_read_b128 v[172:175], v130 offset:2048
	ds_read_b128 v[176:179], v130 offset:4096
	ds_read_b128 v[180:183], v130 offset:6144
	ds_read_b128 v[184:187], v130 offset:8192
	ds_read_b128 v[188:191], v130 offset:10240
	ds_read_b128 v[228:231], v130 offset:12288
	global_load_lds_dwordx4 v200, s[86:87]
	global_load_lds_dwordx4 v201, s[86:87] offset:1024
	global_load_lds_dwordx4 v202, s[86:87] offset:2048
	global_load_lds_dwordx4 v203, s[86:87] offset:3072
	s_add_u32 m0, m0, 0x1000
	s_nop 0
	global_load_lds_dwordx4 v204, s[86:87]
	global_load_lds_dwordx4 v205, s[86:87] offset:1024
	global_load_lds_dwordx4 v206, s[86:87] offset:2048
	global_load_lds_dwordx4 v207, s[86:87] offset:3072
	s_waitcnt lgkmcnt(7)
	s_barrier
; DEVI void lds_barrier() { asm volatile("s_waitcnt lgkmcnt(0)\n\ts_barrier" ::: "memory"); }
; #define SSTORE2(P, buf_) do { \
;     *(uint4*)(wA + (buf_) * 256 * GS2) = P##a0; *(uint4*)(wA + (buf_) * 256 * GS2 + 64 * GS2) = P##a1; \
;     *(uint4*)(wA + (buf_) * 256 * GS2 + 128 * GS2) = P##a2; *(uint4*)(wA + (buf_) * 256 * GS2 + 192 * GS2) = P##a3; \
;     *(uint4*)(wB + (buf_) * 128 * GS2) = P##b0; *(uint4*)(wB + (buf_) * 128 * GS2 + 64 * GS2) = P##b1; } while (0)
; DEVI void gemm_kloop2(const bf16_t* __restrict__ A, size_t lda, const bf16_t* __restrict__ Bt, size_t ldb,
;                       const bf16_t* __restrict__ nA, size_t nlda, const bf16_t* __restrict__ nBt, size_t nldb,
;                       bool first, bf16_t* smem, f32x4 (&acc)[8][4]) {
;     ...
; #pragma unroll 1
;   for (int kt = 0; kt < nk - 2; kt += 2) {
;     COMPUTE2(0, GLOAD2(x, gA, gB, lda, ldb, kt + 1));
;     SSTORE2(x, 1);
;     lds_barrier();
;     COMPUTE2(1, GLOAD2(x, gA, gB, lda, ldb, kt + 2));
;     SSTORE2(x, 0);
;     lds_barrier();
;   }
	s_mov_b32 m0, s53
	s_nop 0
	global_load_lds_dwordx4 v208, s[56:57]
	global_load_lds_dwordx4 v209, s[56:57] offset:1024
	global_load_lds_dwordx4 v210, s[56:57] offset:2048
	global_load_lds_dwordx4 v211, s[56:57] offset:3072
	ds_read_b128 v[232:235], v130 offset:14336
	s_waitcnt lgkmcnt(7)
	v_mfma_f32_16x16x32_bf16 v[114:117], v[236:239], v[168:171], v[114:117]
	v_mfma_f32_16x16x32_bf16 v[102:105], v[240:243], v[168:171], v[102:105]
	v_mfma_f32_16x16x32_bf16 v[94:97], v[244:247], v[168:171], v[94:97]
	v_mfma_f32_16x16x32_bf16 v[86:89], v[146:149], v[168:171], v[86:89]
	s_waitcnt lgkmcnt(6)
	v_mfma_f32_16x16x32_bf16 v[126:129], v[236:239], v[172:175], v[126:129]
	v_mfma_f32_16x16x32_bf16 v[122:125], v[240:243], v[172:175], v[122:125]
	ds_read_b128 v[168:171], v131
	v_mfma_f32_16x16x32_bf16 v[118:121], v[244:247], v[172:175], v[118:121]
	v_mfma_f32_16x16x32_bf16 v[110:113], v[146:149], v[172:175], v[110:113]
	s_waitcnt lgkmcnt(6)
	v_mfma_f32_16x16x32_bf16 v[106:109], v[236:239], v[176:179], v[106:109]
	v_mfma_f32_16x16x32_bf16 v[98:101], v[240:243], v[176:179], v[98:101]
	ds_read_b128 v[172:175], v131 offset:2048
	v_mfma_f32_16x16x32_bf16 v[90:93], v[244:247], v[176:179], v[90:93]
	v_mfma_f32_16x16x32_bf16 v[82:85], v[146:149], v[176:179], v[82:85]
	s_waitcnt lgkmcnt(6)
	v_mfma_f32_16x16x32_bf16 v[78:81], v[236:239], v[180:183], v[78:81]
	v_mfma_f32_16x16x32_bf16 v[74:77], v[240:243], v[180:183], v[74:77]
	ds_read_b128 v[176:179], v131 offset:4096
	v_mfma_f32_16x16x32_bf16 v[70:73], v[244:247], v[180:183], v[70:73]
	v_mfma_f32_16x16x32_bf16 v[66:69], v[146:149], v[180:183], v[66:69]
	s_waitcnt lgkmcnt(6)
	v_mfma_f32_16x16x32_bf16 v[62:65], v[236:239], v[184:187], v[62:65]
	v_mfma_f32_16x16x32_bf16 v[58:61], v[240:243], v[184:187], v[58:61]
	ds_read_b128 v[180:183], v131 offset:6144
	v_mfma_f32_16x16x32_bf16 v[54:57], v[244:247], v[184:187], v[54:57]
	v_mfma_f32_16x16x32_bf16 v[50:53], v[146:149], v[184:187], v[50:53]
	s_waitcnt lgkmcnt(6)
	v_mfma_f32_16x16x32_bf16 v[46:49], v[236:239], v[188:191], v[46:49]
	v_mfma_f32_16x16x32_bf16 v[42:45], v[240:243], v[188:191], v[42:45]
	ds_read_b128 v[184:187], v131 offset:8192
	v_mfma_f32_16x16x32_bf16 v[38:41], v[244:247], v[188:191], v[38:41]
	v_mfma_f32_16x16x32_bf16 v[34:37], v[146:149], v[188:191], v[34:37]
	s_waitcnt lgkmcnt(6)
	v_mfma_f32_16x16x32_bf16 v[30:33], v[236:239], v[228:231], v[30:33]
	v_mfma_f32_16x16x32_bf16 v[26:29], v[240:243], v[228:231], v[26:29]
	ds_read_b128 v[188:191], v131 offset:10240
	v_mfma_f32_16x16x32_bf16 v[22:25], v[244:247], v[228:231], v[22:25]
	v_mfma_f32_16x16x32_bf16 v[18:21], v[146:149], v[228:231], v[18:21]
	s_waitcnt lgkmcnt(6)
	v_mfma_f32_16x16x32_bf16 v[14:17], v[236:239], v[232:235], v[14:17]
	v_mfma_f32_16x16x32_bf16 v[10:13], v[240:243], v[232:235], v[10:13]
	ds_read_b128 v[228:231], v131 offset:12288
	v_mfma_f32_16x16x32_bf16 v[6:9], v[244:247], v[232:235], v[6:9]
	v_mfma_f32_16x16x32_bf16 v[2:5], v[146:149], v[232:235], v[2:5]
	s_waitcnt lgkmcnt(6)
	v_mfma_f32_16x16x32_bf16 v[114:117], v[150:153], v[168:171], v[114:117]
	v_mfma_f32_16x16x32_bf16 v[102:105], v[154:157], v[168:171], v[102:105]
	ds_read_b128 v[232:235], v131 offset:14336
	v_mfma_f32_16x16x32_bf16 v[94:97], v[158:161], v[168:171], v[94:97]
	v_mfma_f32_16x16x32_bf16 v[86:89], v[162:165], v[168:171], v[86:89]
	s_add_u32 s86, s86, 0x80
	s_waitcnt lgkmcnt(6)
	v_mfma_f32_16x16x32_bf16 v[126:129], v[150:153], v[172:175], v[126:129]
	v_mfma_f32_16x16x32_bf16 v[122:125], v[154:157], v[172:175], v[122:125]
	v_mfma_f32_16x16x32_bf16 v[118:121], v[158:161], v[172:175], v[118:121]
	v_mfma_f32_16x16x32_bf16 v[110:113], v[162:165], v[172:175], v[110:113]
	s_addc_u32 s87, s87, 0
	s_waitcnt lgkmcnt(5)
	v_mfma_f32_16x16x32_bf16 v[106:109], v[150:153], v[176:179], v[106:109]
	v_mfma_f32_16x16x32_bf16 v[98:101], v[154:157], v[176:179], v[98:101]
	v_mfma_f32_16x16x32_bf16 v[90:93], v[158:161], v[176:179], v[90:93]
	v_mfma_f32_16x16x32_bf16 v[82:85], v[162:165], v[176:179], v[82:85]
	s_add_u32 s56, s56, 0x80
	s_waitcnt lgkmcnt(4)
	v_mfma_f32_16x16x32_bf16 v[78:81], v[150:153], v[180:183], v[78:81]
	v_mfma_f32_16x16x32_bf16 v[74:77], v[154:157], v[180:183], v[74:77]
	v_mfma_f32_16x16x32_bf16 v[70:73], v[158:161], v[180:183], v[70:73]
	v_mfma_f32_16x16x32_bf16 v[66:69], v[162:165], v[180:183], v[66:69]
	s_addc_u32 s57, s57, 0
	s_waitcnt lgkmcnt(3)
	v_mfma_f32_16x16x32_bf16 v[62:65], v[150:153], v[184:187], v[62:65]
	v_mfma_f32_16x16x32_bf16 v[58:61], v[154:157], v[184:187], v[58:61]
	v_mfma_f32_16x16x32_bf16 v[54:57], v[158:161], v[184:187], v[54:57]
	v_mfma_f32_16x16x32_bf16 v[50:53], v[162:165], v[184:187], v[50:53]
	s_xor_b32 s50, s50, 0x8000
	s_waitcnt lgkmcnt(2)
	v_mfma_f32_16x16x32_bf16 v[46:49], v[150:153], v[188:191], v[46:49]
	v_mfma_f32_16x16x32_bf16 v[42:45], v[154:157], v[188:191], v[42:45]
	v_mfma_f32_16x16x32_bf16 v[38:41], v[158:161], v[188:191], v[38:41]
	v_mfma_f32_16x16x32_bf16 v[34:37], v[162:165], v[188:191], v[34:37]
	s_add_u32 s65, s65, 1
	s_waitcnt lgkmcnt(1)
	v_mfma_f32_16x16x32_bf16 v[30:33], v[150:153], v[228:231], v[30:33]
	v_mfma_f32_16x16x32_bf16 v[26:29], v[154:157], v[228:231], v[26:29]
	v_mfma_f32_16x16x32_bf16 v[22:25], v[158:161], v[228:231], v[22:25]
	v_mfma_f32_16x16x32_bf16 v[18:21], v[162:165], v[228:231], v[18:21]
	s_cmp_eq_u32 s65, 15
	s_waitcnt lgkmcnt(0)
	v_mfma_f32_16x16x32_bf16 v[14:17], v[150:153], v[232:235], v[14:17]
	v_mfma_f32_16x16x32_bf16 v[10:13], v[154:157], v[232:235], v[10:13]
	v_mfma_f32_16x16x32_bf16 v[6:9], v[158:161], v[232:235], v[6:9]
	v_mfma_f32_16x16x32_bf16 v[2:5], v[162:165], v[232:235], v[2:5]
	s_cselect_b64 s[86:87], s[58:59], s[86:87]
	s_cselect_b64 s[56:57], s[60:61], s[56:57]
	s_cmp_lt_u32 s65, 16
	s_cbranch_scc1 .Lg2_loop
	s_setprio 0
	s_nop 7
	s_nop 3
	v_add_u32_e32 v130, s36, v142
	s_cmpk_gt_i32 s34, 0x87f
	v_ashrrev_i32_e32 v131, 31, v130
	s_mov_b64 s[2:3], -1
	s_cbranch_scc1 .LBB0_633
	s_andn2_b64 vcc, exec, s[2:3]
	s_cbranch_vccnz .LBB0_626
	s_branch .LBB0_634

; DEVI void phase_gemm_big(const Params& p, int mode, bf16_t* smem) {
;     ...
;   for (int L = li; L < per_xcd; L += nli) {
;     const int mg = L / (8 * NT), rem = L % (8 * NT), nt = rem >> 3, mt = xcd * 40 + mg * 8 + (rem & 7), m0 = mt * 256, n0 = nt * 128;
;     const int Ln = L + nli < per_xcd ? L + nli : L;
;     const int mgn = Ln / (8 * NT), remn = Ln % (8 * NT), m0n = (xcd * 40 + mgn * 8 + (remn & 7)) * 256, n0n = (remn >> 3) * 128;
.Lg3_go:
	s_add_u32 s86, s42, 0x80
	s_addc_u32 s87, s43, 0
	s_add_u32 s56, s44, 0x80
	s_addc_u32 s57, s45, 0
	s_add_i32 s35, s41, s83
	s_cmpk_gt_i32 s35, 0x4ff
	s_cselect_b64 s[38:39], -1, 0
	s_cmpk_lt_i32 s35, 0x500
	s_cselect_b32 s2, s35, s41
	s_ashr_i32 s3, s2, 31
	s_lshr_b32 s3, s3, 24
	s_add_i32 s3, s2, s3
	s_and_b32 s37, s3, 0xffffff00
	s_lshr_b32 s3, s3, 5
	s_sub_i32 s2, s2, s37
	s_and_b32 s3, s3, 0x7fffff8
	s_add_i32 s3, s3, s40
	s_and_b32 s37, s2, 7
	s_or_b32 s3, s3, s37
	s_lshl_b32 s37, s2, 4
	s_lshl_b32 s2, s3, 8
	s_ashr_i32 s3, s2, 31
	s_and_b32 s42, s37, 0xffffff80
	s_lshl_b64 s[2:3], s[2:3], 11
	s_add_u32 s2, s20, s2
	s_addc_u32 s3, s21, s3
	s_ashr_i32 s43, s42, 31
	s_lshl_b64 s[42:43], s[42:43], 11
	s_add_u32 s42, s0, s42
	s_addc_u32 s43, s1, s43
	s_mov_b64 s[58:59], s[2:3]
	s_mov_b64 s[60:61], s[42:43]
	s_mov_b32 s65, 0
	s_bitcmp1_b32 s41, 5
	s_cbranch_scc0 .Lg3_np
	s_setprio 1

.Lg3_wd:
	s_barrier
	v_add_u32_e32 v130, s50, v212
	v_add_u32_e32 v131, s50, v213
	s_xor_b32 s16, s50, 0x8000
	s_add_u32 m0, s16, s52
	ds_read_b128 v[236:239], v192
	ds_read_b128 v[240:243], v192 offset:2048
	ds_read_b128 v[244:247], v192 offset:4096
	ds_read_b128 v[146:149], v192 offset:6144
	ds_read_b128 v[150:153], v193
	ds_read_b128 v[154:157], v193 offset:2048
	ds_read_b128 v[158:161], v193 offset:4096
	ds_read_b128 v[162:165], v193 offset:6144
	ds_read_b128 v[168:171], v130
	ds_read_b128 v[172:175], v130 offset:2048
	ds_read_b128 v[176:179], v130 offset:4096
	ds_read_b128 v[180:183], v130 offset:6144
	ds_read_b128 v[184:187], v130 offset:8192
	ds_read_b128 v[188:191], v130 offset:10240
	ds_read_b128 v[228:231], v130 offset:12288
	global_load_lds_dwordx4 v200, s[86:87]
	global_load_lds_dwordx4 v201, s[86:87] offset:1024
	global_load_lds_dwordx4 v202, s[86:87] offset:2048
	global_load_lds_dwordx4 v203, s[86:87] offset:3072
	s_add_u32 m0, m0, 0x1000
	s_nop 0
	global_load_lds_dwordx4 v204, s[86:87]
	global_load_lds_dwordx4 v205, s[86:87] offset:1024
	global_load_lds_dwordx4 v206, s[86:87] offset:2048
	global_load_lds_dwordx4 v207, s[86:87] offset:3072
	s_waitcnt lgkmcnt(7)
	s_barrier
; DEVI void lds_barrier() { asm volatile("s_waitcnt lgkmcnt(0)\n\ts_barrier" ::: "memory"); }
; #define SSTORE2(P, buf_) do { \
;     *(uint4*)(wA + (buf_) * 256 * GS2) = P##a0; *(uint4*)(wA + (buf_) * 256 * GS2 + 64 * GS2) = P##a1; \
;     *(uint4*)(wA + (buf_) * 256 * GS2 + 128 * GS2) = P##a2; *(uint4*)(wA + (buf_) * 256 * GS2 + 192 * GS2) = P##a3; \
;     *(uint4*)(wB + (buf_) * 128 * GS2) = P##b0; *(uint4*)(wB + (buf_) * 128 * GS2 + 64 * GS2) = P##b1; } while (0)
; DEVI void gemm_kloop2(const bf16_t* __restrict__ A, size_t lda, const bf16_t* __restrict__ Bt, size_t ldb,
;                       const bf16_t* __restrict__ nA, size_t nlda, const bf16_t* __restrict__ nBt, size_t nldb,
;                       bool first, bf16_t* smem, f32x4 (&acc)[8][4]) {
;     ...
; #pragma unroll 1
;   for (int kt = 0; kt < nk - 2; kt += 2) {
;     COMPUTE2(0, GLOAD2(x, gA, gB, lda, ldb, kt + 1));
;     SSTORE2(x, 1);
;     lds_barrier();
;     COMPUTE2(1, GLOAD2(x, gA, gB, lda, ldb, kt + 2));
;     SSTORE2(x, 0);
;     lds_barrier();
;   }
	s_mov_b32 m0, s53
	s_nop 0
	global_load_lds_dwordx4 v208, s[56:57]
	global_load_lds_dwordx4 v209, s[56:57] offset:1024
	global_load_lds_dwordx4 v210, s[56:57] offset:2048
	global_load_lds_dwordx4 v211, s[56:57] offset:3072
	ds_read_b128 v[232:235], v130 offset:14336
	s_waitcnt lgkmcnt(7)
	v_mfma_f32_16x16x32_bf16 v[114:117], v[236:239], v[168:171], v[114:117]
	v_mfma_f32_16x16x32_bf16 v[102:105], v[240:243], v[168:171], v[102:105]
	v_mfma_f32_16x16x32_bf16 v[94:97], v[244:247], v[168:171], v[94:97]
	v_mfma_f32_16x16x32_bf16 v[86:89], v[146:149], v[168:171], v[86:89]
	s_waitcnt lgkmcnt(6)
	v_mfma_f32_16x16x32_bf16 v[126:129], v[236:239], v[172:175], v[126:129]
	v_mfma_f32_16x16x32_bf16 v[122:125], v[240:243], v[172:175], v[122:125]
	ds_read_b128 v[168:171], v131
	v_mfma_f32_16x16x32_bf16 v[118:121], v[244:247], v[172:175], v[118:121]
	v_mfma_f32_16x16x32_bf16 v[110:113], v[146:149], v[172:175], v[110:113]
	s_waitcnt lgkmcnt(6)
	v_mfma_f32_16x16x32_bf16 v[106:109], v[236:239], v[176:179], v[106:109]
	v_mfma_f32_16x16x32_bf16 v[98:101], v[240:243], v[176:179], v[98:101]
	ds_read_b128 v[172:175], v131 offset:2048
	v_mfma_f32_16x16x32_bf16 v[90:93], v[244:247], v[176:179], v[90:93]
	v_mfma_f32_16x16x32_bf16 v[82:85], v[146:149], v[176:179], v[82:85]
	s_waitcnt lgkmcnt(6)
	v_mfma_f32_16x16x32_bf16 v[78:81], v[236:239], v[180:183], v[78:81]
	v_mfma_f32_16x16x32_bf16 v[74:77], v[240:243], v[180:183], v[74:77]
	ds_read_b128 v[176:179], v131 offset:4096
	v_mfma_f32_16x16x32_bf16 v[70:73], v[244:247], v[180:183], v[70:73]
	v_mfma_f32_16x16x32_bf16 v[66:69], v[146:149], v[180:183], v[66:69]
	s_waitcnt lgkmcnt(6)
	v_mfma_f32_16x16x32_bf16 v[62:65], v[236:239], v[184:187], v[62:65]
	v_mfma_f32_16x16x32_bf16 v[58:61], v[240:243], v[184:187], v[58:61]
	ds_read_b128 v[180:183], v131 offset:6144
	v_mfma_f32_16x16x32_bf16 v[54:57], v[244:247], v[184:187], v[54:57]
	v_mfma_f32_16x16x32_bf16 v[50:53], v[146:149], v[184:187], v[50:53]
	s_waitcnt lgkmcnt(6)
	v_mfma_f32_16x16x32_bf16 v[46:49], v[236:239], v[188:191], v[46:49]
	v_mfma_f32_16x16x32_bf16 v[42:45], v[240:243], v[188:191], v[42:45]
	ds_read_b128 v[184:187], v131 offset:8192
	v_mfma_f32_16x16x32_bf16 v[38:41], v[244:247], v[188:191], v[38:41]
	v_mfma_f32_16x16x32_bf16 v[34:37], v[146:149], v[188:191], v[34:37]
	s_waitcnt lgkmcnt(6)
	v_mfma_f32_16x16x32_bf16 v[30:33], v[236:239], v[228:231], v[30:33]
	v_mfma_f32_16x16x32_bf16 v[26:29], v[240:243], v[228:231], v[26:29]
	ds_read_b128 v[188:191], v131 offset:10240
	v_mfma_f32_16x16x32_bf16 v[22:25], v[244:247], v[228:231], v[22:25]
	v_mfma_f32_16x16x32_bf16 v[18:21], v[146:149], v[228:231], v[18:21]
	s_waitcnt lgkmcnt(6)
	v_mfma_f32_16x16x32_bf16 v[14:17], v[236:239], v[232:235], v[14:17]
	v_mfma_f32_16x16x32_bf16 v[10:13], v[240:243], v[232:235], v[10:13]
	ds_read_b128 v[228:231], v131 offset:12288
	v_mfma_f32_16x16x32_bf16 v[6:9], v[244:247], v[232:235], v[6:9]
	v_mfma_f32_16x16x32_bf16 v[2:5], v[146:149], v[232:235], v[2:5]
	s_waitcnt lgkmcnt(6)
	v_mfma_f32_16x16x32_bf16 v[114:117], v[150:153], v[168:171], v[114:117]
	v_mfma_f32_16x16x32_bf16 v[102:105], v[154:157], v[168:171], v[102:105]
	ds_read_b128 v[232:235], v131 offset:14336
	v_mfma_f32_16x16x32_bf16 v[94:97], v[158:161], v[168:171], v[94:97]
	v_mfma_f32_16x16x32_bf16 v[86:89], v[162:165], v[168:171], v[86:89]
	s_add_u32 s86, s86, 0x80
	s_waitcnt lgkmcnt(6)
	v_mfma_f32_16x16x32_bf16 v[126:129], v[150:153], v[172:175], v[126:129]
	v_mfma_f32_16x16x32_bf16 v[122:125], v[154:157], v[172:175], v[122:125]
	v_mfma_f32_16x16x32_bf16 v[118:121], v[158:161], v[172:175], v[118:121]
	v_mfma_f32_16x16x32_bf16 v[110:113], v[162:165], v[172:175], v[110:113]
	s_addc_u32 s87, s87, 0
	s_waitcnt lgkmcnt(5)
	v_mfma_f32_16x16x32_bf16 v[106:109], v[150:153], v[176:179], v[106:109]
	v_mfma_f32_16x16x32_bf16 v[98:101], v[154:157], v[176:179], v[98:101]
	v_mfma_f32_16x16x32_bf16 v[90:93], v[158:161], v[176:179], v[90:93]
	v_mfma_f32_16x16x32_bf16 v[82:85], v[162:165], v[176:179], v[82:85]
	s_add_u32 s56, s56, 0x80
	s_waitcnt lgkmcnt(4)
	v_mfma_f32_16x16x32_bf16 v[78:81], v[150:153], v[180:183], v[78:81]
	v_mfma_f32_16x16x32_bf16 v[74:77], v[154:157], v[180:183], v[74:77]
	v_mfma_f32_16x16x32_bf16 v[70:73], v[158:161], v[180:183], v[70:73]
	v_mfma_f32_16x16x32_bf16 v[66:69], v[162:165], v[180:183], v[66:69]
	s_addc_u32 s57, s57, 0
	s_waitcnt lgkmcnt(3)
	v_mfma_f32_16x16x32_bf16 v[62:65], v[150:153], v[184:187], v[62:65]
	v_mfma_f32_16x16x32_bf16 v[58:61], v[154:157], v[184:187], v[58:61]
	v_mfma_f32_16x16x32_bf16 v[54:57], v[158:161], v[184:187], v[54:57]
	v_mfma_f32_16x16x32_bf16 v[50:53], v[162:165], v[184:187], v[50:53]
	s_xor_b32 s50, s50, 0x8000
	s_waitcnt lgkmcnt(2)
	v_mfma_f32_16x16x32_bf16 v[46:49], v[150:153], v[188:191], v[46:49]
	v_mfma_f32_16x16x32_bf16 v[42:45], v[154:157], v[188:191], v[42:45]
	v_mfma_f32_16x16x32_bf16 v[38:41], v[158:161], v[188:191], v[38:41]
	v_mfma_f32_16x16x32_bf16 v[34:37], v[162:165], v[188:191], v[34:37]
	s_add_u32 s65, s65, 1
	s_waitcnt lgkmcnt(1)
	v_mfma_f32_16x16x32_bf16 v[30:33], v[150:153], v[228:231], v[30:33]
	v_mfma_f32_16x16x32_bf16 v[26:29], v[154:157], v[228:231], v[26:29]
	v_mfma_f32_16x16x32_bf16 v[22:25], v[158:161], v[228:231], v[22:25]
	v_mfma_f32_16x16x32_bf16 v[18:21], v[162:165], v[228:231], v[18:21]
	s_cmp_eq_u32 s65, 15
	s_waitcnt lgkmcnt(0)
	v_mfma_f32_16x16x32_bf16 v[14:17], v[150:153], v[232:235], v[14:17]
	v_mfma_f32_16x16x32_bf16 v[10:13], v[154:157], v[232:235], v[10:13]
	v_mfma_f32_16x16x32_bf16 v[6:9], v[158:161], v[232:235], v[6:9]
	v_mfma_f32_16x16x32_bf16 v[2:5], v[162:165], v[232:235], v[2:5]
	s_cselect_b64 s[86:87], s[58:59], s[86:87]
	s_cselect_b64 s[56:57], s[60:61], s[56:57]
	s_cmp_lt_u32 s65, 16
	s_cbranch_scc1 .Lg3_loop
	s_setprio 0
	s_nop 7
	s_nop 3
	v_add_u32_e32 v130, s36, v142
	s_cmpk_gt_i32 s34, 0xbff
	v_ashrrev_i32_e32 v131, 31, v130
	s_mov_b64 s[2:3], -1
	s_cbranch_scc1 .LBB0_1119
	s_andn2_b64 vcc, exec, s[2:3]
	s_cbranch_vccnz .LBB0_1112
	s_branch .LBB0_1120
